# HID stored tile-major [pm][kt][256][64] so P9 A K-tile reads are contiguous 32KB
# speedup vs baseline: 1.0009x; 1.0009x over previous
; #define PG8_STAGE(bufoff, gbase, voff) do { _Pragma("unroll") for (int _i = 0; _i < 2; ++_i) \
;         __builtin_amdgcn_global_load_lds((const unsigned*)((const char*)(gbase) + (voff)[_i]), (PG8_LAS unsigned*)(lds + (bufoff) + ldsw + _i * 8192), 16, 0, 0); } while (0)
; #define PG8_WAIT_V(n) asm volatile("s_waitcnt vmcnt(" #n ")" ::: "memory")
; #define PG8_BAR __builtin_amdgcn_s_barrier()
; template <class Epi, class Sched, bool ALIGN_EPI = false, bool SP2 = false>
; __device__ __forceinline__ void gemm_phase(PG8_LAS unsigned char* lds, const Gemm g, const Sched& S, const Epi& E) {
;     ...
;     for (int i = 0; i < 2; ++i) { int R, C; stage_rc(tid * 16 + i * 8192, R, C); const int Rb = Epi::PERM ? ((R & ~31) + perm32(R & 31)) : R;
;         voffA[i] = (unsigned)(R * K + C) * 2u; voffB[i] = (unsigned)(Rb * K + C) * 2u; }
;     const size_t kstep = (size_t)(BK * 2);
;     const size_t hstep = (size_t)HALF * K * 2;
;     const size_t tstep = 2 * hstep;
;     const unsigned ldsw = (unsigned)wid * 1024u;
;     const int aoff = lds_byte(wr * 64 + fr, fq * 8), boff = lds_byte(wc * 32 + fr, fq * 8);
;     ...
;         PG8_STAGE(PG8_SB(1, 0), cB + kstep, voffB); PG8_STAGE(PG8_SA(1, 0), cA + kstep, voffA); PG8_STAGE(PG8_SB(1, 1), cB + hstep + kstep, voffB);
;         PG8_WAIT_V(6); PG8_BAR;
.LBB0_1010:
	s_mov_b64 s[36:37], 0x80
	s_add_i32 m0, s50, 0x18000
	v_lshl_add_u64 v[8:9], v[8:9], 0, s[36:37]
	s_waitcnt vmcnt(2)
	s_barrier
	global_load_lds_dwordx4 v[8:9], off
	v_lshl_add_u64 v[4:5], v[4:5], 0, s[36:37]
	s_add_i32 m0, s50, 0x1a000
	s_add_i32 s55, s50, 0x8000
	global_load_lds_dwordx4 v[4:5], off
	v_lshl_add_u64 v[4:5], v[6:7], 0, s[36:37]
	s_mov_b32 m0, s55
	s_add_i32 s56, s50, 0xa000
	global_load_lds_dwordx4 v[4:5], off
	v_lshl_add_u64 v[4:5], v[10:11], 0, s[36:37]
	s_mov_b32 m0, s56
	v_lshl_add_u64 v[2:3], v[2:3], 0, s[36:37]
	global_load_lds_dwordx4 v[4:5], off
	s_add_i32 m0, s50, 0x1c000
	v_lshl_add_u64 v[0:1], v[0:1], 0, s[36:37]
	global_load_lds_dwordx4 v[2:3], off
	s_add_i32 m0, s50, 0x1e000
	s_lshr_b32 s1, s1, 26
	global_load_lds_dwordx4 v[0:1], off
	v_lshrrev_b32_e32 v1, 1, v12
	v_and_b32_e32 v1, 24, v1
	v_and_b32_e32 v0, 15, v12
	v_lshlrev_b32_e32 v2, 1, v1
	s_add_i32 s1, s0, s1
	v_lshl_or_b32 v144, s7, 6, v0
	v_lshl_or_b32 v0, v0, 6, v2
	v_lshlrev_b32_e32 v2, 2, v12
	s_ashr_i32 s57, s1, 6
	s_lshl_b32 s1, s7, 13
	v_and_b32_e32 v2, 32, v2
	v_bitop3_b32 v3, v0, s1, v2 bitop3:0xde
	s_lshl_b32 s1, s6, 5
	s_sext_i32_i16 s67, s4
	s_and_b32 s4, s1, 0x60
	s_lshl_b32 s1, s4, 7
	v_bitop3_b32 v145, v0, s1, v2 bitop3:0xde
	v_add_u32_e32 v0, v18, v16
	s_cmp_gt_i32 s0, 63
	v_or_b32_e32 v146, s4, v1
	v_add_lshl_u32 v0, v0, v17, 1
	v_mov_b32_e32 v1, v133
	s_cselect_b64 s[0:1], -1, 0
	s_add_i32 s58, s57, -2
	v_lshl_add_u64 v[136:137], s[10:11], 0, v[0:1]
	v_add_u32_e32 v0, v15, v13
	s_waitcnt vmcnt(6)
	s_cmpk_lt_u32 s5, 0x100
	v_add_lshl_u32 v0, v0, v14, 1
	s_cselect_b64 s[38:39], -1, 0
	v_lshl_add_u64 v[138:139], s[10:11], 0, v[0:1]
	v_cndmask_b32_e64 v0, 0, 1, s[0:1]
	s_add_i32 s61, 0, 0x10000
	s_add_i32 s62, 0, 0x14000
	s_ashr_i32 s59, s30, 31
	s_mov_b32 s60, s30
	v_mov_b64_e32 v[140:141], 0x1600
	v_mov_b64_e32 v[142:143], 0x15ff
	v_add_u32_e32 v147, s61, v145
	v_add_u32_e32 v148, s62, v145
	v_add_u32_e32 v149, 0, v3
	s_movk_i32 s63, 0x80
	v_cmp_ne_u32_e64 s[4:5], 1, v0
	s_barrier
	s_waitcnt vmcnt(0)
	s_branch .LBB0_1013

; __device__ __forceinline__ u32x4 pack8(const f32x4 a, const f32x4 b) { u32x4 w; w.x = cvt_pk_bf16(a[0], a[1]); w.y = cvt_pk_bf16(a[2], a[3]); w.z = cvt_pk_bf16(b[0], b[1]); w.w = cvt_pk_bf16(b[2], b[3]); return w; }
; #define EPI_ROWLOOP _Pragma("unroll") for (int ai = 0; ai < 2; ++ai) _Pragma("unroll") for (int m = 0; m < 4; ++m)
; __device__ __forceinline__ float sigm(float x) { return __builtin_amdgcn_rcpf(1.0f + __builtin_amdgcn_exp2f(x * -1.4426950408889634f)); }
; __device__ __forceinline__ float sigm_new(float x) { return __builtin_amdgcn_rcpf(1.0f + __builtin_amdgcn_exp2f(x * -1.4426950408889634f)); }
; __device__ __forceinline__ f32x4 sigm4_new(const f32x4 v) { f32x4 o; o[0] = sigm_new(v[0]); o[1] = sigm_new(v[1]); o[2] = sigm_new(v[2]); o[3] = sigm_new(v[3]); return o; }
; __device__ __forceinline__ f32x4 silu4_new(const f32x4 v) { return v * sigm4_new(v); }
;     __device__ __forceinline__ void operator()(const f32x4 (&acc)[2][2][4][2], const Unit& u, int wr, int wc, int fr, int fq) const {
;         const int row0 = u.pm * BM + wr * 64 + fr, c0 = u.pn * 128 + wc * 32 + 8 * fq;
;         EPI_ROWLOOP { const int r = row0 + ai * HALF + m * 16;
;             *(u32x4*)(HID + (size_t)r * ldh + c0) = pack8(silu4_new(acc[ai][0][m][0]) * acc[ai][1][m][0], silu4_new(acc[ai][0][m][1]) * acc[ai][1][m][1]); }
;     }
.LBB0_1024:
	v_mul_f32_e32 v151, 0xbfb8aa3b, v124
	v_exp_f32_e32 v151, v151
	v_mul_f32_e32 v153, 0xbfb8aa3b, v125
	v_exp_f32_e32 v155, v153
	v_and_b32_e32 v152, 64, v146
	v_lshlrev_b32_e32 v152, 8, v152
	v_and_or_b32 v152, v146, 63, v152
	v_add_f32_e32 v151, 1.0, v151
	v_rcp_f32_e32 v154, v151
	v_add_f32_e32 v151, 1.0, v155
	v_mul_f32_e32 v155, 0xbfb8aa3b, v126
	v_exp_f32_e32 v156, v155
	v_mul_f32_e32 v155, 0xbfb8aa3b, v127
	v_exp_f32_e32 v157, v155
	v_rcp_f32_e32 v155, v151
	v_add_f32_e32 v151, 1.0, v156
	v_rcp_f32_e32 v156, v151
	v_add_f32_e32 v151, 1.0, v157
	v_rcp_f32_e32 v157, v151
	v_mul_f32_e32 v151, 0xbfb8aa3b, v116
	v_pk_mul_f32 v[124:125], v[124:125], v[154:155]
	v_exp_f32_e32 v151, v151
	v_mul_f32_e32 v154, 0xbfb8aa3b, v117
	v_exp_f32_e32 v155, v154
	v_pk_mul_f32 v[126:127], v[126:127], v[156:157]
	v_add_f32_e32 v151, 1.0, v151
	v_rcp_f32_e32 v154, v151
	v_add_f32_e32 v151, 1.0, v155
	v_mul_f32_e32 v155, 0xbfb8aa3b, v118
	v_exp_f32_e32 v156, v155
	v_mul_f32_e32 v155, 0xbfb8aa3b, v119
	v_exp_f32_e32 v157, v155
	v_rcp_f32_e32 v155, v151
	v_add_f32_e32 v151, 1.0, v156
	v_rcp_f32_e32 v156, v151
	v_add_f32_e32 v151, 1.0, v157
	v_rcp_f32_e32 v157, v151
	v_pk_mul_f32 v[116:117], v[116:117], v[154:155]
	v_mov_b32_e32 v150, v144
	v_pk_mul_f32 v[112:113], v[112:113], v[116:117]
	v_pk_mul_f32 v[118:119], v[118:119], v[156:157]
	v_ashrrev_i32_e32 v153, 31, v152
	v_pk_mul_f32 v[120:121], v[120:121], v[124:125]
	v_pk_mul_f32 v[114:115], v[114:115], v[118:119]
	v_cvt_pk_bf16_f32 v118, v112, v113
	s_mul_i32 s100, s66, 0x160000
	s_lshl_b32 s101, s67, 16
	s_add_u32 s100, s100, s101
	s_add_u32 s100, s24, s100
	s_addc_u32 s101, s25, 0
	v_mov_b64_e32 v[112:113], s[100:101]
	v_pk_mul_f32 v[122:123], v[122:123], v[126:127]
	v_cvt_pk_bf16_f32 v116, v120, v121
	v_cvt_pk_bf16_f32 v119, v114, v115
	v_mad_i64_i32 v[120:121], s[42:43], v150, s63, v[112:113]
	v_lshlrev_b64 v[114:115], 1, v[152:153]
	v_cvt_pk_bf16_f32 v117, v122, v123
	v_lshl_add_u64 v[120:121], v[120:121], 0, v[114:115]
	global_store_dwordx4 v[120:121], v[116:119], off nt
	v_or_b32_e32 v120, 16, v150
	s_and_b64 vcc, exec, s[6:7]
	v_mul_f32_e32 v116, 0xbfb8aa3b, v108
	v_mul_f32_e32 v117, 0xbfb8aa3b, v109
	v_mul_f32_e32 v118, 0xbfb8aa3b, v110
	v_mul_f32_e32 v119, 0xbfb8aa3b, v111
	v_exp_f32_e32 v116, v116
	v_exp_f32_e32 v117, v117
	v_exp_f32_e32 v118, v118
	v_exp_f32_e32 v119, v119
	v_add_f32_e32 v116, 1.0, v116
	v_add_f32_e32 v117, 1.0, v117
	v_add_f32_e32 v118, 1.0, v118
	v_add_f32_e32 v119, 1.0, v119
	v_rcp_f32_e32 v116, v116
	v_rcp_f32_e32 v117, v117
	v_rcp_f32_e32 v118, v118
	v_rcp_f32_e32 v119, v119
	s_mov_b64 s[6:7], -1
	v_pk_mul_f32 v[108:109], v[108:109], v[116:117]
	v_mul_f32_e32 v116, 0xbfb8aa3b, v100
	v_mul_f32_e32 v117, 0xbfb8aa3b, v101
	v_pk_mul_f32 v[110:111], v[110:111], v[118:119]
	v_mul_f32_e32 v118, 0xbfb8aa3b, v102
	v_mul_f32_e32 v119, 0xbfb8aa3b, v103
	v_exp_f32_e32 v116, v116
	v_exp_f32_e32 v117, v117
	v_exp_f32_e32 v118, v118
	v_exp_f32_e32 v119, v119
	v_add_f32_e32 v116, 1.0, v116
	v_add_f32_e32 v117, 1.0, v117
	v_add_f32_e32 v118, 1.0, v118
	v_add_f32_e32 v119, 1.0, v119
	v_rcp_f32_e32 v116, v116
	v_rcp_f32_e32 v117, v117
	v_rcp_f32_e32 v118, v118
	v_rcp_f32_e32 v119, v119
	v_pk_mul_f32 v[106:107], v[106:107], v[110:111]
	v_pk_mul_f32 v[100:101], v[100:101], v[116:117]
	v_pk_mul_f32 v[104:105], v[104:105], v[108:109]
	v_pk_mul_f32 v[102:103], v[102:103], v[118:119]
	s_nop 0
	v_pk_mul_f32 v[102:103], v[98:99], v[102:103]
	v_pk_mul_f32 v[98:99], v[96:97], v[100:101]
	v_mad_i64_i32 v[100:101], s[42:43], v120, s63, v[112:113]
	v_cvt_pk_bf16_f32 v96, v104, v105
	v_cvt_pk_bf16_f32 v97, v106, v107
	v_cvt_pk_bf16_f32 v98, v98, v99
	v_cvt_pk_bf16_f32 v99, v102, v103
	v_lshl_add_u64 v[100:101], v[100:101], 0, v[114:115]
	global_store_dwordx4 v[100:101], v[96:99], off nt
	v_or_b32_e32 v100, 32, v150
	s_nop 0
	v_mul_f32_e32 v96, 0xbfb8aa3b, v92
	v_mul_f32_e32 v97, 0xbfb8aa3b, v93
	v_mul_f32_e32 v98, 0xbfb8aa3b, v94
	v_mul_f32_e32 v99, 0xbfb8aa3b, v95
	v_exp_f32_e32 v96, v96
	v_exp_f32_e32 v97, v97
	v_exp_f32_e32 v98, v98
	v_exp_f32_e32 v99, v99
	v_add_f32_e32 v96, 1.0, v96
	v_add_f32_e32 v97, 1.0, v97
	v_add_f32_e32 v98, 1.0, v98
	v_add_f32_e32 v99, 1.0, v99
	v_rcp_f32_e32 v96, v96
	v_rcp_f32_e32 v97, v97
	v_rcp_f32_e32 v98, v98
	v_rcp_f32_e32 v99, v99
	v_pk_mul_f32 v[92:93], v[92:93], v[96:97]
	v_mul_f32_e32 v96, 0xbfb8aa3b, v84
	v_mul_f32_e32 v97, 0xbfb8aa3b, v85
	v_pk_mul_f32 v[94:95], v[94:95], v[98:99]
	v_mul_f32_e32 v98, 0xbfb8aa3b, v86
	v_mul_f32_e32 v99, 0xbfb8aa3b, v87
	v_exp_f32_e32 v96, v96
	v_exp_f32_e32 v97, v97
	v_exp_f32_e32 v98, v98
	v_exp_f32_e32 v99, v99
	v_add_f32_e32 v96, 1.0, v96
	v_add_f32_e32 v97, 1.0, v97
	v_add_f32_e32 v98, 1.0, v98
	v_add_f32_e32 v99, 1.0, v99
	v_rcp_f32_e32 v96, v96
	v_rcp_f32_e32 v97, v97
	v_rcp_f32_e32 v98, v98
	v_rcp_f32_e32 v99, v99
	v_pk_mul_f32 v[90:91], v[90:91], v[94:95]
	v_pk_mul_f32 v[84:85], v[84:85], v[96:97]
	v_pk_mul_f32 v[88:89], v[88:89], v[92:93]
	v_pk_mul_f32 v[86:87], v[86:87], v[98:99]
	s_nop 0
	v_pk_mul_f32 v[86:87], v[82:83], v[86:87]
	v_pk_mul_f32 v[82:83], v[80:81], v[84:85]
	v_mad_i64_i32 v[84:85], s[42:43], v100, s63, v[112:113]
	v_cvt_pk_bf16_f32 v80, v88, v89
	v_cvt_pk_bf16_f32 v81, v90, v91
	v_cvt_pk_bf16_f32 v82, v82, v83
	v_cvt_pk_bf16_f32 v83, v86, v87
	v_lshl_add_u64 v[84:85], v[84:85], 0, v[114:115]
	global_store_dwordx4 v[84:85], v[80:83], off nt
	v_or_b32_e32 v84, 48, v150
	s_nop 0
	v_mul_f32_e32 v80, 0xbfb8aa3b, v76
	v_mul_f32_e32 v81, 0xbfb8aa3b, v77
	v_mul_f32_e32 v82, 0xbfb8aa3b, v78
	v_mul_f32_e32 v83, 0xbfb8aa3b, v79
	v_exp_f32_e32 v80, v80
	v_exp_f32_e32 v81, v81
	v_exp_f32_e32 v82, v82
; __device__ __forceinline__ u32x4 pack8(const f32x4 a, const f32x4 b) { u32x4 w; w.x = cvt_pk_bf16(a[0], a[1]); w.y = cvt_pk_bf16(a[2], a[3]); w.z = cvt_pk_bf16(b[0], b[1]); w.w = cvt_pk_bf16(b[2], b[3]); return w; }
; #define EPI_ROWLOOP _Pragma("unroll") for (int ai = 0; ai < 2; ++ai) _Pragma("unroll") for (int m = 0; m < 4; ++m)
; __device__ __forceinline__ float sigm(float x) { return __builtin_amdgcn_rcpf(1.0f + __builtin_amdgcn_exp2f(x * -1.4426950408889634f)); }
; __device__ __forceinline__ float sigm_new(float x) { return __builtin_amdgcn_rcpf(1.0f + __builtin_amdgcn_exp2f(x * -1.4426950408889634f)); }
; __device__ __forceinline__ f32x4 sigm4_new(const f32x4 v) { f32x4 o; o[0] = sigm_new(v[0]); o[1] = sigm_new(v[1]); o[2] = sigm_new(v[2]); o[3] = sigm_new(v[3]); return o; }
; __device__ __forceinline__ f32x4 silu4_new(const f32x4 v) { return v * sigm4_new(v); }
;     __device__ __forceinline__ void operator()(const f32x4 (&acc)[2][2][4][2], const Unit& u, int wr, int wc, int fr, int fq) const {
;     ...
;         EPI_ROWLOOP { const int r = row0 + ai * HALF + m * 16;
;             *(u32x4*)(HID + (size_t)r * ldh + c0) = pack8(silu4_new(acc[ai][0][m][0]) * acc[ai][1][m][0], silu4_new(acc[ai][0][m][1]) * acc[ai][1][m][1]); }
;     }
	v_exp_f32_e32 v83, v83
	v_add_f32_e32 v80, 1.0, v80
	v_add_f32_e32 v81, 1.0, v81
	v_add_f32_e32 v82, 1.0, v82
	v_add_f32_e32 v83, 1.0, v83
	v_rcp_f32_e32 v80, v80
	v_rcp_f32_e32 v81, v81
	v_rcp_f32_e32 v82, v82
	v_rcp_f32_e32 v83, v83
	v_pk_mul_f32 v[76:77], v[76:77], v[80:81]
	v_mul_f32_e32 v80, 0xbfb8aa3b, v68
	v_mul_f32_e32 v81, 0xbfb8aa3b, v69
	v_pk_mul_f32 v[78:79], v[78:79], v[82:83]
	v_mul_f32_e32 v82, 0xbfb8aa3b, v70
	v_mul_f32_e32 v83, 0xbfb8aa3b, v71
	v_exp_f32_e32 v80, v80
	v_exp_f32_e32 v81, v81
	v_exp_f32_e32 v82, v82
	v_exp_f32_e32 v83, v83
	v_add_f32_e32 v80, 1.0, v80
	v_add_f32_e32 v81, 1.0, v81
	v_add_f32_e32 v82, 1.0, v82
	v_add_f32_e32 v83, 1.0, v83
	v_rcp_f32_e32 v80, v80
	v_rcp_f32_e32 v81, v81
	v_rcp_f32_e32 v82, v82
	v_rcp_f32_e32 v83, v83
	v_pk_mul_f32 v[74:75], v[74:75], v[78:79]
	v_pk_mul_f32 v[68:69], v[68:69], v[80:81]
	v_pk_mul_f32 v[72:73], v[72:73], v[76:77]
	v_pk_mul_f32 v[70:71], v[70:71], v[82:83]
	s_nop 0
	v_pk_mul_f32 v[70:71], v[66:67], v[70:71]
	v_pk_mul_f32 v[66:67], v[64:65], v[68:69]
	v_mad_i64_i32 v[68:69], s[42:43], v84, s63, v[112:113]
	v_cvt_pk_bf16_f32 v64, v72, v73
	v_cvt_pk_bf16_f32 v65, v74, v75
	v_cvt_pk_bf16_f32 v66, v66, v67
	v_cvt_pk_bf16_f32 v67, v70, v71
	v_lshl_add_u64 v[68:69], v[68:69], 0, v[114:115]
	global_store_dwordx4 v[68:69], v[64:67], off nt
	v_add_u32_e32 v68, 0x80, v150
	s_nop 0
	v_mul_f32_e32 v64, 0xbfb8aa3b, v60
	v_mul_f32_e32 v65, 0xbfb8aa3b, v61
	v_mul_f32_e32 v66, 0xbfb8aa3b, v62
	v_mul_f32_e32 v67, 0xbfb8aa3b, v63
	v_exp_f32_e32 v64, v64
	v_exp_f32_e32 v65, v65
	v_exp_f32_e32 v66, v66
	v_exp_f32_e32 v67, v67
	v_add_f32_e32 v64, 1.0, v64
	v_add_f32_e32 v65, 1.0, v65
	v_add_f32_e32 v66, 1.0, v66
	v_add_f32_e32 v67, 1.0, v67
	v_rcp_f32_e32 v64, v64
	v_rcp_f32_e32 v65, v65
	v_rcp_f32_e32 v66, v66
	v_rcp_f32_e32 v67, v67
	v_pk_mul_f32 v[60:61], v[60:61], v[64:65]
	v_mul_f32_e32 v64, 0xbfb8aa3b, v52
	v_mul_f32_e32 v65, 0xbfb8aa3b, v53
	v_pk_mul_f32 v[62:63], v[62:63], v[66:67]
	v_mul_f32_e32 v66, 0xbfb8aa3b, v54
	v_mul_f32_e32 v67, 0xbfb8aa3b, v55
	v_exp_f32_e32 v64, v64
	v_exp_f32_e32 v65, v65
	v_exp_f32_e32 v66, v66
	v_exp_f32_e32 v67, v67
	v_add_f32_e32 v64, 1.0, v64
	v_add_f32_e32 v65, 1.0, v65
	v_add_f32_e32 v66, 1.0, v66
	v_add_f32_e32 v67, 1.0, v67
	v_rcp_f32_e32 v64, v64
	v_rcp_f32_e32 v65, v65
	v_rcp_f32_e32 v66, v66
	v_rcp_f32_e32 v67, v67
	v_pk_mul_f32 v[58:59], v[58:59], v[62:63]
	v_pk_mul_f32 v[52:53], v[52:53], v[64:65]
	v_pk_mul_f32 v[56:57], v[56:57], v[60:61]
	v_pk_mul_f32 v[54:55], v[54:55], v[66:67]
	s_nop 0
	v_pk_mul_f32 v[54:55], v[50:51], v[54:55]
	v_pk_mul_f32 v[50:51], v[48:49], v[52:53]
	v_mad_i64_i32 v[52:53], s[42:43], v68, s63, v[112:113]
	v_cvt_pk_bf16_f32 v48, v56, v57
	v_cvt_pk_bf16_f32 v49, v58, v59
	v_cvt_pk_bf16_f32 v50, v50, v51
	v_cvt_pk_bf16_f32 v51, v54, v55
	v_lshl_add_u64 v[52:53], v[52:53], 0, v[114:115]
	global_store_dwordx4 v[52:53], v[48:51], off nt
	v_add_u32_e32 v52, 0x90, v150
	s_nop 0
	v_mul_f32_e32 v48, 0xbfb8aa3b, v44
	v_mul_f32_e32 v49, 0xbfb8aa3b, v45
	v_mul_f32_e32 v50, 0xbfb8aa3b, v46
	v_mul_f32_e32 v51, 0xbfb8aa3b, v47
	v_exp_f32_e32 v48, v48
	v_exp_f32_e32 v49, v49
	v_exp_f32_e32 v50, v50
	v_exp_f32_e32 v51, v51
	v_add_f32_e32 v48, 1.0, v48
	v_add_f32_e32 v49, 1.0, v49
	v_add_f32_e32 v50, 1.0, v50
	v_add_f32_e32 v51, 1.0, v51
	v_rcp_f32_e32 v48, v48
	v_rcp_f32_e32 v49, v49
	v_rcp_f32_e32 v50, v50
	v_rcp_f32_e32 v51, v51
	v_pk_mul_f32 v[44:45], v[44:45], v[48:49]
	v_mul_f32_e32 v48, 0xbfb8aa3b, v36
	v_mul_f32_e32 v49, 0xbfb8aa3b, v37
	v_pk_mul_f32 v[46:47], v[46:47], v[50:51]
	v_mul_f32_e32 v50, 0xbfb8aa3b, v38
	v_mul_f32_e32 v51, 0xbfb8aa3b, v39
	v_exp_f32_e32 v48, v48
	v_exp_f32_e32 v49, v49
	v_exp_f32_e32 v50, v50
	v_exp_f32_e32 v51, v51
	v_add_f32_e32 v48, 1.0, v48
	v_add_f32_e32 v49, 1.0, v49
	v_add_f32_e32 v50, 1.0, v50
	v_add_f32_e32 v51, 1.0, v51
	v_rcp_f32_e32 v48, v48
; __device__ __forceinline__ u32x4 pack8(const f32x4 a, const f32x4 b) { u32x4 w; w.x = cvt_pk_bf16(a[0], a[1]); w.y = cvt_pk_bf16(a[2], a[3]); w.z = cvt_pk_bf16(b[0], b[1]); w.w = cvt_pk_bf16(b[2], b[3]); return w; }
; #define EPI_ROWLOOP _Pragma("unroll") for (int ai = 0; ai < 2; ++ai) _Pragma("unroll") for (int m = 0; m < 4; ++m)
; __device__ __forceinline__ float sigm(float x) { return __builtin_amdgcn_rcpf(1.0f + __builtin_amdgcn_exp2f(x * -1.4426950408889634f)); }
; __device__ __forceinline__ float sigm_new(float x) { return __builtin_amdgcn_rcpf(1.0f + __builtin_amdgcn_exp2f(x * -1.4426950408889634f)); }
; __device__ __forceinline__ f32x4 sigm4_new(const f32x4 v) { f32x4 o; o[0] = sigm_new(v[0]); o[1] = sigm_new(v[1]); o[2] = sigm_new(v[2]); o[3] = sigm_new(v[3]); return o; }
; __device__ __forceinline__ f32x4 silu4_new(const f32x4 v) { return v * sigm4_new(v); }
;     __device__ __forceinline__ void operator()(const f32x4 (&acc)[2][2][4][2], const Unit& u, int wr, int wc, int fr, int fq) const {
;     ...
;         EPI_ROWLOOP { const int r = row0 + ai * HALF + m * 16;
;             *(u32x4*)(HID + (size_t)r * ldh + c0) = pack8(silu4_new(acc[ai][0][m][0]) * acc[ai][1][m][0], silu4_new(acc[ai][0][m][1]) * acc[ai][1][m][1]); }
;     }
	v_rcp_f32_e32 v49, v49
	v_rcp_f32_e32 v50, v50
	v_rcp_f32_e32 v51, v51
	v_pk_mul_f32 v[42:43], v[42:43], v[46:47]
	v_pk_mul_f32 v[36:37], v[36:37], v[48:49]
	v_pk_mul_f32 v[40:41], v[40:41], v[44:45]
	v_pk_mul_f32 v[38:39], v[38:39], v[50:51]
	s_nop 0
	v_pk_mul_f32 v[38:39], v[34:35], v[38:39]
	v_pk_mul_f32 v[34:35], v[32:33], v[36:37]
	v_mad_i64_i32 v[36:37], s[42:43], v52, s63, v[112:113]
	v_cvt_pk_bf16_f32 v32, v40, v41
	v_cvt_pk_bf16_f32 v33, v42, v43
	v_cvt_pk_bf16_f32 v34, v34, v35
	v_cvt_pk_bf16_f32 v35, v38, v39
	v_lshl_add_u64 v[36:37], v[36:37], 0, v[114:115]
	global_store_dwordx4 v[36:37], v[32:35], off nt
	v_add_u32_e32 v36, 0xa0, v150
	s_nop 0
	v_mul_f32_e32 v32, 0xbfb8aa3b, v28
	v_mul_f32_e32 v33, 0xbfb8aa3b, v29
	v_mul_f32_e32 v34, 0xbfb8aa3b, v30
	v_mul_f32_e32 v35, 0xbfb8aa3b, v31
	v_exp_f32_e32 v32, v32
	v_exp_f32_e32 v33, v33
	v_exp_f32_e32 v34, v34
	v_exp_f32_e32 v35, v35
	v_add_f32_e32 v32, 1.0, v32
	v_add_f32_e32 v33, 1.0, v33
	v_add_f32_e32 v34, 1.0, v34
	v_add_f32_e32 v35, 1.0, v35
	v_rcp_f32_e32 v32, v32
	v_rcp_f32_e32 v33, v33
	v_rcp_f32_e32 v34, v34
	v_rcp_f32_e32 v35, v35
	v_pk_mul_f32 v[28:29], v[28:29], v[32:33]
	v_mul_f32_e32 v32, 0xbfb8aa3b, v20
	v_mul_f32_e32 v33, 0xbfb8aa3b, v21
	v_pk_mul_f32 v[30:31], v[30:31], v[34:35]
	v_mul_f32_e32 v34, 0xbfb8aa3b, v22
	v_mul_f32_e32 v35, 0xbfb8aa3b, v23
	v_exp_f32_e32 v32, v32
	v_exp_f32_e32 v33, v33
	v_exp_f32_e32 v34, v34
	v_exp_f32_e32 v35, v35
	v_add_f32_e32 v32, 1.0, v32
	v_add_f32_e32 v33, 1.0, v33
	v_add_f32_e32 v34, 1.0, v34
	v_add_f32_e32 v35, 1.0, v35
	v_rcp_f32_e32 v32, v32
	v_rcp_f32_e32 v33, v33
	v_rcp_f32_e32 v34, v34
	v_rcp_f32_e32 v35, v35
	v_pk_mul_f32 v[26:27], v[26:27], v[30:31]
	v_pk_mul_f32 v[20:21], v[20:21], v[32:33]
	v_pk_mul_f32 v[24:25], v[24:25], v[28:29]
	v_pk_mul_f32 v[22:23], v[22:23], v[34:35]
	s_nop 0
	v_pk_mul_f32 v[22:23], v[18:19], v[22:23]
	v_pk_mul_f32 v[18:19], v[16:17], v[20:21]
	v_mad_i64_i32 v[20:21], s[42:43], v36, s63, v[112:113]
	v_cvt_pk_bf16_f32 v16, v24, v25
	v_cvt_pk_bf16_f32 v17, v26, v27
	v_cvt_pk_bf16_f32 v18, v18, v19
	v_cvt_pk_bf16_f32 v19, v22, v23
	v_lshl_add_u64 v[20:21], v[20:21], 0, v[114:115]
	global_store_dwordx4 v[20:21], v[16:19], off nt
	v_add_u32_e32 v20, 0xb0, v150
	s_nop 0
	v_mul_f32_e32 v16, 0xbfb8aa3b, v12
	v_mul_f32_e32 v17, 0xbfb8aa3b, v13
	v_mul_f32_e32 v18, 0xbfb8aa3b, v14
	v_mul_f32_e32 v19, 0xbfb8aa3b, v15
	v_exp_f32_e32 v16, v16
	v_exp_f32_e32 v17, v17
	v_exp_f32_e32 v18, v18
	v_exp_f32_e32 v19, v19
	v_add_f32_e32 v16, 1.0, v16
	v_add_f32_e32 v17, 1.0, v17
	v_add_f32_e32 v18, 1.0, v18
	v_add_f32_e32 v19, 1.0, v19
	v_rcp_f32_e32 v16, v16
	v_rcp_f32_e32 v17, v17
	v_rcp_f32_e32 v18, v18
	v_rcp_f32_e32 v19, v19
	v_pk_mul_f32 v[12:13], v[12:13], v[16:17]
	v_mul_f32_e32 v16, 0xbfb8aa3b, v4
	v_mul_f32_e32 v17, 0xbfb8aa3b, v5
	v_pk_mul_f32 v[14:15], v[14:15], v[18:19]
	v_mul_f32_e32 v18, 0xbfb8aa3b, v6
	v_mul_f32_e32 v19, 0xbfb8aa3b, v7
	v_exp_f32_e32 v16, v16
	v_exp_f32_e32 v17, v17
	v_exp_f32_e32 v18, v18
	v_exp_f32_e32 v19, v19
	v_add_f32_e32 v16, 1.0, v16
	v_add_f32_e32 v17, 1.0, v17
	v_add_f32_e32 v18, 1.0, v18
	v_add_f32_e32 v19, 1.0, v19
	v_rcp_f32_e32 v16, v16
	v_rcp_f32_e32 v17, v17
	v_rcp_f32_e32 v18, v18
	v_rcp_f32_e32 v19, v19
	v_pk_mul_f32 v[10:11], v[10:11], v[14:15]
	v_pk_mul_f32 v[4:5], v[4:5], v[16:17]
	v_pk_mul_f32 v[8:9], v[8:9], v[12:13]
	v_pk_mul_f32 v[6:7], v[6:7], v[18:19]
	s_nop 0
	v_pk_mul_f32 v[6:7], v[2:3], v[6:7]
	v_pk_mul_f32 v[2:3], v[0:1], v[4:5]
	v_mad_i64_i32 v[4:5], s[42:43], v20, s63, v[112:113]
	v_cvt_pk_bf16_f32 v0, v8, v9
	v_cvt_pk_bf16_f32 v1, v10, v11
	v_cvt_pk_bf16_f32 v2, v2, v3
	v_cvt_pk_bf16_f32 v3, v6, v7
	v_lshl_add_u64 v[4:5], v[4:5], 0, v[114:115]
	global_store_dwordx4 v[4:5], v[0:3], off nt
	s_cbranch_vccnz .LBB0_1012
	s_andn2_b64 vcc, exec, s[14:15]
	s_cbranch_vccnz .LBB0_1011
	s_barrier
	s_branch .LBB0_1011

; #define PG8_STAGE(bufoff, gbase, voff) do { _Pragma("unroll") for (int _i = 0; _i < 2; ++_i) \
;         __builtin_amdgcn_global_load_lds((const unsigned*)((const char*)(gbase) + (voff)[_i]), (PG8_LAS unsigned*)(lds + (bufoff) + ldsw + _i * 8192), 16, 0, 0); } while (0)
; #define PG8_WAIT_V(n) asm volatile("s_waitcnt vmcnt(" #n ")" ::: "memory")
; #define PG8_BAR __builtin_amdgcn_s_barrier()
; template <class Epi, class Sched, bool ALIGN_EPI = false, bool SP2 = false>
; __device__ __forceinline__ void gemm_phase(PG8_LAS unsigned char* lds, const Gemm g, const Sched& S, const Epi& E) {
;     ...
;     for (int i = 0; i < 2; ++i) { int R, C; stage_rc(tid * 16 + i * 8192, R, C); const int Rb = Epi::PERM ? ((R & ~31) + perm32(R & 31)) : R;
;         voffA[i] = (unsigned)(R * K + C) * 2u; voffB[i] = (unsigned)(Rb * K + C) * 2u; }
;     const size_t kstep = (size_t)(BK * 2);
;     const size_t hstep = (size_t)HALF * K * 2;
;     const size_t tstep = 2 * hstep;
;     const unsigned ldsw = (unsigned)wid * 1024u;
;     const int aoff = lds_byte(wr * 64 + fr, fq * 8), boff = lds_byte(wc * 32 + fr, fq * 8);
;     ...
;         PG8_STAGE(PG8_SB(0, 0), cB, voffB); PG8_STAGE(PG8_SB(0, 1), cB + hstep, voffB); PG8_STAGE(PG8_SA(0, 0), cA, voffA); PG8_STAGE(PG8_SA(0, 1), cA + hstep, voffA);
;         if (wr == 1) PG8_BAR;
;         PG8_WAIT_V(2); PG8_BAR;
;         PG8_STAGE(PG8_SB(1, 0), cB + kstep, voffB); PG8_STAGE(PG8_SA(1, 0), cA + kstep, voffA); PG8_STAGE(PG8_SB(1, 1), cB + hstep + kstep, voffB);
;         PG8_WAIT_V(6); PG8_BAR;
.LBB0_1086:
	s_add_u32 s10, s28, 0x38900000
	s_addc_u32 s11, s29, 0
	s_and_b64 vcc, exec, s[8:9]
	s_cbranch_vccnz .LBB0_1127
	v_bfe_i32 v2, v12, 27, 1
	v_lshlrev_b32_e32 v0, 4, v12
	v_lshrrev_b32_e32 v2, 22, v2
	v_add_u32_e32 v2, v0, v2
	v_and_b32_e32 v2, 0xfffffc00, v2
	v_sub_u32_e32 v2, v0, v2
	v_ashrrev_i32_e32 v1, 31, v12
	v_lshrrev_b32_e32 v3, 4, v2
	v_lshrrev_b32_e32 v1, 26, v1
	v_bitop3_b32 v2, v3, v2, 32 bitop3:0x6c
	v_add_u32_e32 v1, v12, v1
	v_ashrrev_i32_e32 v4, 31, v2
	v_ashrrev_i32_e32 v1, 6, v1
	v_lshrrev_b32_e32 v4, 26, v4
	v_lshlrev_b32_e32 v3, 3, v1
	v_add_u32_e32 v4, v2, v4
	v_and_b32_e32 v3, -16, v3
	v_ashrrev_i32_e32 v5, 6, v4
	v_lshlrev_b32_e32 v1, 5, v1
	v_add_u32_e32 v3, v5, v3
	v_and_b32_e32 v13, 32, v1
	v_and_b32_e32 v1, 0xc0, v4
	v_sub_u32_e32 v1, v2, v1
	v_mov_b32_e32 v2, 1
	v_lshlrev_b32_e32 v4, 1, v3
	v_lshrrev_b32_e32 v6, 2, v3
	v_and_b32_e32 v5, 3, v5
	s_mov_b32 s1, 0x7fffffe0
	v_ashrrev_i16_sdwa v1, v2, sext(v1) dst_sel:DWORD dst_unused:UNUSED_PAD src0_sel:DWORD src1_sel:BYTE_0
	v_and_b32_e32 v4, 24, v4
	v_and_b32_e32 v6, 4, v6
	v_and_or_b32 v5, v3, s1, v5
	v_bfe_i32 v14, v1, 0, 16
	v_or3_b32 v4, v5, v6, v4
	v_add_u32_e32 v1, v13, v14
	v_lshlrev_b32_e32 v15, 6, v3
	v_mul_lo_u32 v3, v4, s0
	v_add_u32_e32 v0, 0x2000, v0
	v_add_lshl_u32 v128, v1, v15, 1
	v_add_lshl_u32 v130, v3, v1, 1
	v_ashrrev_i32_e32 v1, 31, v0
	v_lshrrev_b32_e32 v1, 22, v1
	v_add_u32_e32 v1, v0, v1
	v_ashrrev_i32_e32 v1, 10, v1
	v_mul_i32_i24_e32 v3, 0x400, v1
	v_sub_u32_e32 v0, v0, v3
	v_lshrrev_b32_e32 v3, 4, v0
	v_bitop3_b32 v0, v3, v0, 32 bitop3:0x6c
	v_ashrrev_i32_e32 v4, 31, v0
	v_lshrrev_b32_e32 v4, 26, v4
	v_lshlrev_b32_e32 v3, 3, v1
	v_add_u32_e32 v4, v0, v4
	v_and_b32_e32 v3, -16, v3
	v_ashrrev_i32_e32 v5, 6, v4
	v_lshlrev_b32_e32 v1, 5, v1
	s_add_u32 s3, s28, 0x1c80000
	v_add_u32_e32 v3, v5, v3
	v_and_b32_e32 v16, 32, v1
	v_and_b32_e32 v1, 0xc0, v4
	v_and_b32_e32 v4, 3, v5
	s_addc_u32 s48, s29, 0
	v_and_or_b32 v4, v3, s1, v4
	s_ashr_i32 s1, s0, 31
	s_lshl_b64 s[12:13], s[0:1], 9
	s_ashr_i32 s7, s67, 31
	s_ashr_i32 s16, s14, 31
	s_mul_i32 s7, s12, s7
	s_mul_hi_u32 s15, s12, s67
	s_lshr_b64 s[34:35], s[0:1], 23
	s_mul_i32 s16, s12, s16
	s_mul_hi_u32 s17, s12, s14
	s_ashr_i32 s4, s6, 6
	s_add_i32 s7, s15, s7
	s_mul_i32 s15, s34, s67
	s_add_i32 s16, s17, s16
	s_mul_i32 s17, s34, s14
	v_sub_u32_e32 v0, v0, v1
	s_ashr_i32 s5, s6, 8
	s_lshl_b64 s[8:9], s[0:1], 8
	s_lshl_b32 s49, s4, 10
	s_add_i32 s7, s7, s15
	s_add_i32 s16, s16, s17
	s_mul_i32 s17, s12, s14
	v_ashrrev_i16_sdwa v0, v2, sext(v0) dst_sel:DWORD dst_unused:UNUSED_PAD src0_sel:DWORD src1_sel:BYTE_0
	v_lshlrev_b32_e32 v1, 1, v3
	v_lshrrev_b32_e32 v2, 2, v3
	s_add_u32 s46, s3, s17
	v_and_b32_e32 v1, 24, v1
	v_and_b32_e32 v2, 4, v2
	s_addc_u32 s47, s48, s16
	s_add_i32 s50, s49, 0
	v_bfe_i32 v17, v0, 0, 16
	v_or3_b32 v1, v4, v2, v1
	s_add_i32 m0, s50, 0x10000
	v_add_u32_e32 v0, v16, v17
	v_mul_lo_u32 v1, v1, s0
	global_load_lds_dwordx4 v130, s[46:47]
	s_add_i32 m0, s50, 0x12000
	v_add_lshl_u32 v134, v1, v0, 1
	s_add_u32 s34, s46, s8
	global_load_lds_dwordx4 v134, s[46:47]
	s_addc_u32 s35, s47, s9
	s_add_i32 m0, s50, 0x14000
	s_mul_i32 s15, s12, s67
	global_load_lds_dwordx4 v130, s[34:35]
	s_add_i32 m0, s50, 0x16000
	s_add_u32 s44, s24, s15
	s_addc_u32 s45, s25, s7
	s_add_i32 s51, s50, 0x2000
	v_lshlrev_b32_e32 v18, 6, v3
	global_load_lds_dwordx4 v134, s[34:35]
	s_mov_b32 m0, s50
	s_add_u32 s36, s44, 0x4000
	v_add_lshl_u32 v132, v0, v18, 1
	global_load_lds_dwordx4 v128, s[44:45]
	s_mov_b32 m0, s51
	s_addc_u32 s37, s45, 0
	s_add_i32 s52, s50, 0x4000
	global_load_lds_dwordx4 v132, s[44:45]
	s_mov_b32 m0, s52
	s_add_i32 s53, s50, 0x6000
	global_load_lds_dwordx4 v128, s[36:37]
	s_mov_b32 m0, s53
	v_mov_b32_e32 v131, 0
	global_load_lds_dwordx4 v132, s[36:37]
	v_mov_b32_e32 v135, v131
	v_mov_b32_e32 v129, v131
	v_mov_b32_e32 v133, v131
	s_cmp_eq_u32 s5, 1
	s_mov_b32 s15, 0
	v_lshl_add_u64 v[8:9], s[46:47], 0, v[130:131]
	v_lshl_add_u64 v[4:5], s[46:47], 0, v[134:135]
	v_lshl_add_u64 v[2:3], s[34:35], 0, v[130:131]
	v_lshl_add_u64 v[0:1], s[34:35], 0, v[134:135]
	v_lshl_add_u64 v[6:7], s[44:45], 0, v[128:129]
	s_cselect_b64 s[34:35], -1, 0
	s_cmp_lg_u32 s5, 1
	v_lshl_add_u64 v[10:11], s[44:45], 0, v[132:133]
	s_cbranch_scc1 .LBB0_1089
	s_barrier
.LBB0_1089:
	s_mov_b64 s[36:37], 0x80
	s_mov_b64 s[100:101], 0x8000
	s_add_i32 m0, s50, 0x18000
	v_lshl_add_u64 v[8:9], v[8:9], 0, s[36:37]
	s_waitcnt vmcnt(2)
	s_barrier
	global_load_lds_dwordx4 v[8:9], off
	v_lshl_add_u64 v[4:5], v[4:5], 0, s[36:37]
	s_add_i32 m0, s50, 0x1a000
	s_add_i32 s54, s50, 0x8000
	global_load_lds_dwordx4 v[4:5], off
	v_lshl_add_u64 v[4:5], v[6:7], 0, s[100:101]
	s_mov_b32 m0, s54
	s_add_i32 s55, s50, 0xa000
	global_load_lds_dwordx4 v[4:5], off
	v_lshl_add_u64 v[4:5], v[10:11], 0, s[100:101]
	s_mov_b32 m0, s55
	v_lshl_add_u64 v[2:3], v[2:3], 0, s[36:37]
	global_load_lds_dwordx4 v[4:5], off
	s_add_i32 m0, s50, 0x1c000
	v_lshl_add_u64 v[0:1], v[0:1], 0, s[36:37]
	global_load_lds_dwordx4 v[2:3], off
	s_add_i32 m0, s50, 0x1e000
	s_lshr_b32 s1, s1, 26
	global_load_lds_dwordx4 v[0:1], off
	v_bfe_u32 v1, v12, 4, 2
	v_and_b32_e32 v0, 15, v12
	v_lshlrev_b32_e32 v3, 4, v1
	s_add_i32 s1, s0, s1
	v_lshl_or_b32 v148, s5, 6, v0
	v_lshl_or_b32 v0, v0, 6, v3
	v_lshlrev_b32_e32 v3, 2, v12
	s_and_b32 s56, s4, 3
	s_ashr_i32 s57, s1, 6
	s_lshl_b32 s1, s5, 13
	v_and_b32_e32 v3, 32, v3
	v_bitop3_b32 v4, v0, s1, v3 bitop3:0xde
	s_lshl_b32 s1, s56, 12
	s_cmp_gt_i32 s0, 63
	v_bitop3_b32 v149, v0, s1, v3 bitop3:0xde
	s_cselect_b64 s[38:39], -1, 0
	s_add_i32 s58, s57, -2
	v_add_u32_e32 v0, v15, v13
	v_lshlrev_b32_e32 v2, 3, v1
	s_cmpk_lt_u32 s6, 0x100
	v_cmp_eq_u32_e64 s[6:7], 0, v1
	v_add_lshl_u32 v0, v0, v14, 1
	v_mov_b32_e32 v1, v131
	s_waitcnt vmcnt(6)
	s_mov_b64 s[98:99], 0x4000
	v_lshl_add_u64 v[136:137], s[98:99], 0, v[0:1]
	v_add_u32_e32 v0, v18, v16
	s_cselect_b64 s[40:41], -1, 0
	v_add_lshl_u32 v0, v0, v17, 1
	s_add_i32 s62, 0, 0x10000
	s_add_i32 s63, 0, 0x14000
	v_lshl_or_b32 v150, s56, 5, v2
	s_ashr_i32 s59, s30, 31
	s_mov_b32 s60, s30
	s_ashr_i32 s61, s2, 31
	s_mov_b64 s[98:99], 0x4000
	v_lshl_add_u64 v[138:139], s[98:99], 0, v[0:1]
	v_mov_b64_e32 v[140:141], 0x400
	v_mov_b64_e32 v[142:143], 0x3ff
	v_add_u32_e32 v151, s62, v149
	v_add_u32_e32 v152, s63, v149
	v_add_u32_e32 v153, 0, v4
	v_mbcnt_hi_u32_b32 v154, -1, v234
	s_mov_b32 s64, 0
	s_barrier
	s_branch .LBB0_1092

; #define PG8_STAGE(bufoff, gbase, voff) do { _Pragma("unroll") for (int _i = 0; _i < 2; ++_i) \
;         __builtin_amdgcn_global_load_lds((const unsigned*)((const char*)(gbase) + (voff)[_i]), (PG8_LAS unsigned*)(lds + (bufoff) + ldsw + _i * 8192), 16, 0, 0); } while (0)
; #define PG8_LDA(dst, b, h) do { _Pragma("unroll") for (int m = 0; m < 4; ++m) _Pragma("unroll") for (int k = 0; k < 2; ++k) dst[m][k] = *(const PG8_LAS bf16x8*)(lds + PG8_SA(b, h) + aoff + m * 2048 + k * 1024); } while (0)
; #define PG8_LDB(dst, b, h) do { _Pragma("unroll") for (int n = 0; n < 2; ++n) _Pragma("unroll") for (int k = 0; k < 2; ++k) dst[n][k] = *(const PG8_LAS bf16x8*)(lds + PG8_SB(b, h) + boff + n * 2048 + k * 1024); } while (0)
; #define PG8_MMA(ai, bj, At, Bt) do { __builtin_amdgcn_s_setprio(1); _Pragma("unroll") for (int m = 0; m < 4; ++m) _Pragma("unroll") for (int n = 0; n < 2; ++n) _Pragma("unroll") for (int k = 0; k < 2; ++k) \
;         acc[ai][bj][m][n] = __builtin_amdgcn_mfma_f32_16x16x32_bf16(Bt[n][k], At[m][k], acc[ai][bj][m][n], 0, 0, 0); __builtin_amdgcn_s_setprio(0); } while (0)
; #define PG8_WAIT_V(n) asm volatile("s_waitcnt vmcnt(" #n ")" ::: "memory")
; #define PG8_BAR __builtin_amdgcn_s_barrier()
; template <class Epi, class Sched, bool ALIGN_EPI = false, bool SP2 = false>
; __device__ __forceinline__ void gemm_phase(PG8_LAS unsigned char* lds, const Gemm g, const Sched& S, const Epi& E) {
;     ...
;         for (int t = 0; t < nt; t += 2) {
;             const bool last = (t == nt - 2);
;             const char* a1 = cA + (size_t)(t + 1) * kstep;
;             const char* a2 = last ? nA : cA + (size_t)(t + 2) * kstep; const char* b2 = last ? nB : cB + (size_t)(t + 2) * kstep;
;             const char* a3 = a2 + kstep; const char* b3 = b2 + kstep;
;             if (last && has_next) S.a_ready(nxt);
;             if constexpr (SP2) {
;             PG8_LDB(B0, 0, 0); PG8_LDB(B1, 0, 1); PG8_SCHED; PG8_LDA(At, 0, 0); PG8_STAGE(PG8_SA(1, 1), a1 + hstep, voffA);
;             PG8_WAIT_V(8); PG8_WAIT_L(0); PG8_BAR; PG8_MMA(0, 0, At, B0); PG8_MMA(0, 1, At, B1); PG8_BAR; PG8_SCHED;
;     ...
;         for (int a = 0; a < 2; ++a)
; #pragma unroll
;             for (int b = 0; b < 2; ++b)
; #pragma unroll
;                 for (int m = 0; m < 4; ++m)
; #pragma unroll
;                     for (int n = 0; n < 2; ++n) acc[a][b][m][n] = (f32x4){0.f, 0.f, 0.f, 0.f};
.LBB0_1102:
	v_mov_b32_e32 v127, 0
	s_andn2_b64 vcc, exec, s[38:39]
	v_mov_b32_e32 v126, v127
	v_mov_b32_e32 v125, v127
	v_mov_b32_e32 v124, v127
	v_mov_b32_e32 v123, v127
	v_mov_b32_e32 v122, v127
	v_mov_b32_e32 v121, v127
	v_mov_b32_e32 v120, v127
	v_mov_b32_e32 v111, v127
	v_mov_b32_e32 v110, v127
	v_mov_b32_e32 v109, v127
	v_mov_b32_e32 v108, v127
	v_mov_b32_e32 v107, v127
	v_mov_b32_e32 v106, v127
	v_mov_b32_e32 v105, v127
	v_mov_b32_e32 v104, v127
	v_mov_b32_e32 v95, v127
	v_mov_b32_e32 v94, v127
	v_mov_b32_e32 v93, v127
	v_mov_b32_e32 v92, v127
	v_mov_b32_e32 v91, v127
	v_mov_b32_e32 v90, v127
	v_mov_b32_e32 v89, v127
	v_mov_b32_e32 v88, v127
	v_mov_b32_e32 v79, v127
	v_mov_b32_e32 v78, v127
	v_mov_b32_e32 v77, v127
	v_mov_b32_e32 v76, v127
	v_mov_b32_e32 v75, v127
	v_mov_b32_e32 v74, v127
	v_mov_b32_e32 v73, v127
	v_mov_b32_e32 v72, v127
	v_mov_b32_e32 v119, v127
	v_mov_b32_e32 v118, v127
	v_mov_b32_e32 v117, v127
	v_mov_b32_e32 v116, v127
	v_mov_b32_e32 v115, v127
	v_mov_b32_e32 v114, v127
	v_mov_b32_e32 v113, v127
	v_mov_b32_e32 v112, v127
	v_mov_b32_e32 v103, v127
	v_mov_b32_e32 v102, v127
	v_mov_b32_e32 v101, v127
	v_mov_b32_e32 v100, v127
	v_mov_b32_e32 v99, v127
	v_mov_b32_e32 v98, v127
	v_mov_b32_e32 v97, v127
	v_mov_b32_e32 v96, v127
	v_mov_b32_e32 v87, v127
	v_mov_b32_e32 v86, v127
	v_mov_b32_e32 v85, v127
	v_mov_b32_e32 v84, v127
	v_mov_b32_e32 v83, v127
	v_mov_b32_e32 v82, v127
	v_mov_b32_e32 v81, v127
	v_mov_b32_e32 v80, v127
	v_mov_b32_e32 v71, v127
	v_mov_b32_e32 v70, v127
	v_mov_b32_e32 v69, v127
	v_mov_b32_e32 v68, v127
	v_mov_b32_e32 v67, v127
	v_mov_b32_e32 v66, v127
	v_mov_b32_e32 v65, v127
	v_mov_b32_e32 v64, v127
	v_mov_b32_e32 v63, v127
	v_mov_b32_e32 v62, v127
	v_mov_b32_e32 v61, v127
	v_mov_b32_e32 v60, v127
	v_mov_b32_e32 v59, v127
	v_mov_b32_e32 v58, v127
	v_mov_b32_e32 v57, v127
	v_mov_b32_e32 v56, v127
	v_mov_b32_e32 v47, v127
	v_mov_b32_e32 v46, v127
	v_mov_b32_e32 v45, v127
	v_mov_b32_e32 v44, v127
	v_mov_b32_e32 v43, v127
	v_mov_b32_e32 v42, v127
	v_mov_b32_e32 v41, v127
	v_mov_b32_e32 v40, v127
	v_mov_b32_e32 v31, v127
	v_mov_b32_e32 v30, v127
	v_mov_b32_e32 v29, v127
	v_mov_b32_e32 v28, v127
	v_mov_b32_e32 v27, v127
	v_mov_b32_e32 v26, v127
	v_mov_b32_e32 v25, v127
	v_mov_b32_e32 v24, v127
	v_mov_b32_e32 v15, v127
	v_mov_b32_e32 v14, v127
	v_mov_b32_e32 v13, v127
	v_mov_b32_e32 v12, v127
	v_mov_b32_e32 v11, v127
	v_mov_b32_e32 v10, v127
	v_mov_b32_e32 v9, v127
	v_mov_b32_e32 v8, v127
	v_mov_b32_e32 v55, v127
	v_mov_b32_e32 v54, v127
	v_mov_b32_e32 v53, v127
	v_mov_b32_e32 v52, v127
	v_mov_b32_e32 v51, v127
	v_mov_b32_e32 v50, v127
	v_mov_b32_e32 v49, v127
	v_mov_b32_e32 v48, v127
	v_mov_b32_e32 v39, v127
	v_mov_b32_e32 v38, v127
	v_mov_b32_e32 v37, v127
	v_mov_b32_e32 v36, v127
	v_mov_b32_e32 v35, v127
	v_mov_b32_e32 v34, v127
	v_mov_b32_e32 v33, v127
	v_mov_b32_e32 v32, v127
	v_mov_b32_e32 v23, v127
	v_mov_b32_e32 v22, v127
	v_mov_b32_e32 v21, v127
	v_mov_b32_e32 v20, v127
	v_mov_b32_e32 v19, v127
	v_mov_b32_e32 v18, v127
	v_mov_b32_e32 v17, v127
	v_mov_b32_e32 v16, v127
	v_mov_b32_e32 v7, v127
	v_mov_b32_e32 v6, v127
	s_waitcnt lgkmcnt(0)
	v_mov_b32_e32 v5, v127
	v_mov_b32_e32 v4, v127
	v_mov_b32_e32 v3, v127
	v_mov_b32_e32 v2, v127
	v_mov_b32_e32 v1, v127
	v_mov_b32_e32 v0, v127
	s_cbranch_vccnz .LBB0_1105
	s_add_u32 s44, s44, 0x8000
	s_addc_u32 s45, s45, 0
	s_add_u32 s68, s46, 0x100
	s_addc_u32 s69, s47, 0
	s_mov_b32 s46, 0
.LBB0_1104:
	ds_read_b128 v[144:147], v151
	ds_read_b128 v[156:159], v151 offset:1024
	ds_read_b128 v[160:163], v151 offset:2048
	ds_read_b128 v[164:167], v151 offset:3072
	ds_read_b128 v[168:171], v152
	ds_read_b128 v[172:175], v152 offset:1024
	ds_read_b128 v[176:179], v152 offset:2048
	ds_read_b128 v[180:183], v152 offset:3072
	s_add_i32 s70, s46, 2
	s_add_u32 s16, s44, 0x8000
	s_addc_u32 s17, s45, 0
	s_cmp_eq_u32 s58, s46
	s_cselect_b32 s46, s0, s16
	s_cselect_b32 s47, s1, s17
	s_cselect_b32 s73, s43, s69
	s_cselect_b32 s72, s42, s68
	v_lshl_add_u64 v[218:219], s[44:45], 0, v[136:137]
	s_add_i32 m0, s50, 0xc000
	ds_read_b128 v[184:187], v153
	ds_read_b128 v[188:191], v153 offset:1024
	ds_read_b128 v[192:195], v153 offset:2048
	ds_read_b128 v[196:199], v153 offset:3072
	ds_read_b128 v[202:205], v153 offset:4096
	ds_read_b128 v[206:209], v153 offset:5120
	ds_read_b128 v[210:213], v153 offset:6144
	ds_read_b128 v[214:217], v153 offset:7168
	global_load_lds_dwordx4 v[218:219], off
	v_lshl_add_u64 v[218:219], s[44:45], 0, v[138:139]
	s_add_i32 m0, s50, 0xe000
	s_nop 0
	global_load_lds_dwordx4 v[218:219], off
	s_waitcnt vmcnt(8)
	s_waitcnt lgkmcnt(0)
	s_barrier
; #define PG8_STAGE(bufoff, gbase, voff) do { _Pragma("unroll") for (int _i = 0; _i < 2; ++_i) \
;         __builtin_amdgcn_global_load_lds((const unsigned*)((const char*)(gbase) + (voff)[_i]), (PG8_LAS unsigned*)(lds + (bufoff) + ldsw + _i * 8192), 16, 0, 0); } while (0)
; #define PG8_LDA(dst, b, h) do { _Pragma("unroll") for (int m = 0; m < 4; ++m) _Pragma("unroll") for (int k = 0; k < 2; ++k) dst[m][k] = *(const PG8_LAS bf16x8*)(lds + PG8_SA(b, h) + aoff + m * 2048 + k * 1024); } while (0)
; #define PG8_LDB(dst, b, h) do { _Pragma("unroll") for (int n = 0; n < 2; ++n) _Pragma("unroll") for (int k = 0; k < 2; ++k) dst[n][k] = *(const PG8_LAS bf16x8*)(lds + PG8_SB(b, h) + boff + n * 2048 + k * 1024); } while (0)
; #define PG8_MMA(ai, bj, At, Bt) do { __builtin_amdgcn_s_setprio(1); _Pragma("unroll") for (int m = 0; m < 4; ++m) _Pragma("unroll") for (int n = 0; n < 2; ++n) _Pragma("unroll") for (int k = 0; k < 2; ++k) \
;         acc[ai][bj][m][n] = __builtin_amdgcn_mfma_f32_16x16x32_bf16(Bt[n][k], At[m][k], acc[ai][bj][m][n], 0, 0, 0); __builtin_amdgcn_s_setprio(0); } while (0)
; #define PG8_WAIT_V(n) asm volatile("s_waitcnt vmcnt(" #n ")" ::: "memory")
; #define PG8_WAIT_L(n) asm volatile("s_waitcnt lgkmcnt(" #n ")" ::: "memory")
; #define PG8_BAR __builtin_amdgcn_s_barrier()
; #define PG8_SCHED __builtin_amdgcn_sched_barrier(0)
; template <class Epi, class Sched, bool ALIGN_EPI = false, bool SP2 = false>
; __device__ __forceinline__ void gemm_phase(PG8_LAS unsigned char* lds, const Gemm g, const Sched& S, const Epi& E) {
;     ...
;             PG8_LDB(B0, 0, 0); PG8_LDB(B1, 0, 1); PG8_SCHED; PG8_LDA(At, 0, 0); PG8_STAGE(PG8_SA(1, 1), a1 + hstep, voffA);
;             PG8_WAIT_V(8); PG8_WAIT_L(0); PG8_BAR; PG8_MMA(0, 0, At, B0); PG8_MMA(0, 1, At, B1); PG8_BAR; PG8_SCHED;
;             PG8_LDA(At, 0, 1); PG8_STAGE(PG8_SB(0, 0), b2, voffB); PG8_STAGE(PG8_SB(0, 1), b2 + hstep, voffB); PG8_STAGE(PG8_SA(0, 0), a2, voffA);
;             PG8_WAIT_V(8); PG8_WAIT_L(0); PG8_BAR; PG8_MMA(1, 0, At, B0); PG8_MMA(1, 1, At, B1); PG8_BAR; PG8_SCHED;
	s_setprio 1
	s_waitcnt lgkmcnt(0)
	v_mfma_f32_16x16x32_bf16 v[124:127], v[144:147], v[184:187], v[124:127]
	v_mfma_f32_16x16x32_bf16 v[120:123], v[160:163], v[184:187], v[120:123]
	v_mfma_f32_16x16x32_bf16 v[108:111], v[144:147], v[192:195], v[108:111]
	v_mfma_f32_16x16x32_bf16 v[104:107], v[160:163], v[192:195], v[104:107]
	v_mfma_f32_16x16x32_bf16 v[92:95], v[144:147], v[202:205], v[92:95]
	v_mfma_f32_16x16x32_bf16 v[88:91], v[160:163], v[202:205], v[88:91]
	v_mfma_f32_16x16x32_bf16 v[76:79], v[144:147], v[210:213], v[76:79]
	v_mfma_f32_16x16x32_bf16 v[72:75], v[160:163], v[210:213], v[72:75]
	v_mfma_f32_16x16x32_bf16 v[124:127], v[156:159], v[188:191], v[124:127]
	v_mfma_f32_16x16x32_bf16 v[120:123], v[164:167], v[188:191], v[120:123]
	v_mfma_f32_16x16x32_bf16 v[108:111], v[156:159], v[196:199], v[108:111]
	v_mfma_f32_16x16x32_bf16 v[104:107], v[164:167], v[196:199], v[104:107]
	v_mfma_f32_16x16x32_bf16 v[92:95], v[156:159], v[206:209], v[92:95]
	v_mfma_f32_16x16x32_bf16 v[88:91], v[164:167], v[206:209], v[88:91]
	v_mfma_f32_16x16x32_bf16 v[76:79], v[156:159], v[214:217], v[76:79]
	v_mfma_f32_16x16x32_bf16 v[72:75], v[164:167], v[214:217], v[72:75]
	s_setprio 0
	s_setprio 1
	v_mfma_f32_16x16x32_bf16 v[116:119], v[168:171], v[184:187], v[116:119]
	v_mfma_f32_16x16x32_bf16 v[112:115], v[176:179], v[184:187], v[112:115]
	v_mfma_f32_16x16x32_bf16 v[100:103], v[168:171], v[192:195], v[100:103]
	v_mfma_f32_16x16x32_bf16 v[96:99], v[176:179], v[192:195], v[96:99]
	v_mfma_f32_16x16x32_bf16 v[84:87], v[168:171], v[202:205], v[84:87]
	v_mfma_f32_16x16x32_bf16 v[80:83], v[176:179], v[202:205], v[80:83]
	v_mfma_f32_16x16x32_bf16 v[68:71], v[168:171], v[210:213], v[68:71]
	v_mfma_f32_16x16x32_bf16 v[64:67], v[176:179], v[210:213], v[64:67]
	v_mfma_f32_16x16x32_bf16 v[116:119], v[172:175], v[188:191], v[116:119]
	v_mfma_f32_16x16x32_bf16 v[112:115], v[180:183], v[188:191], v[112:115]
	v_mfma_f32_16x16x32_bf16 v[100:103], v[172:175], v[196:199], v[100:103]
	v_mfma_f32_16x16x32_bf16 v[96:99], v[180:183], v[196:199], v[96:99]
	v_mfma_f32_16x16x32_bf16 v[84:87], v[172:175], v[206:209], v[84:87]
	v_mfma_f32_16x16x32_bf16 v[80:83], v[180:183], v[206:209], v[80:83]
	v_mfma_f32_16x16x32_bf16 v[68:71], v[172:175], v[214:217], v[68:71]
	v_mfma_f32_16x16x32_bf16 v[64:67], v[180:183], v[214:217], v[64:67]
	s_setprio 0
	s_barrier
	s_add_i32 s16, s62, s49
	v_lshl_add_u64 v[218:219], s[72:73], 0, v[130:131]
	s_mov_b32 m0, s16
	ds_read_b128 v[184:187], v153 offset:16384
	ds_read_b128 v[188:191], v153 offset:17408
	ds_read_b128 v[192:195], v153 offset:18432
	ds_read_b128 v[196:199], v153 offset:19456
	ds_read_b128 v[202:205], v153 offset:20480
	ds_read_b128 v[206:209], v153 offset:21504
	ds_read_b128 v[210:213], v153 offset:22528
	ds_read_b128 v[214:217], v153 offset:23552
	global_load_lds_dwordx4 v[218:219], off
	s_add_i32 m0, s16, 0x2000
	v_lshl_add_u64 v[220:221], s[72:73], 0, v[134:135]
	s_add_u32 s72, s72, s8
	s_addc_u32 s73, s73, s9
	s_add_i32 s16, s63, s49
	global_load_lds_dwordx4 v[220:221], off
	v_lshl_add_u64 v[222:223], s[72:73], 0, v[130:131]
	s_mov_b32 m0, s16
	v_lshl_add_u64 v[224:225], s[72:73], 0, v[134:135]
	global_load_lds_dwordx4 v[222:223], off
	s_add_i32 m0, s16, 0x2000
	v_lshl_add_u64 v[226:227], s[46:47], 0, v[128:129]
	global_load_lds_dwordx4 v[224:225], off
	s_mov_b32 m0, s50
	v_lshl_add_u64 v[228:229], s[46:47], 0, v[132:133]
	global_load_lds_dwordx4 v[226:227], off
	s_mov_b32 m0, s51
	s_nop 0
	global_load_lds_dwordx4 v[228:229], off
	s_waitcnt vmcnt(8)
	s_waitcnt lgkmcnt(0)
	s_barrier
	s_setprio 1
	s_waitcnt lgkmcnt(0)
	v_mfma_f32_16x16x32_bf16 v[60:63], v[144:147], v[184:187], v[60:63]
	v_mfma_f32_16x16x32_bf16 v[56:59], v[160:163], v[184:187], v[56:59]
	v_mfma_f32_16x16x32_bf16 v[44:47], v[144:147], v[192:195], v[44:47]
	v_mfma_f32_16x16x32_bf16 v[40:43], v[160:163], v[192:195], v[40:43]
	v_mfma_f32_16x16x32_bf16 v[28:31], v[144:147], v[202:205], v[28:31]
	v_mfma_f32_16x16x32_bf16 v[24:27], v[160:163], v[202:205], v[24:27]
	v_mfma_f32_16x16x32_bf16 v[12:15], v[144:147], v[210:213], v[12:15]
	v_mfma_f32_16x16x32_bf16 v[8:11], v[160:163], v[210:213], v[8:11]
	v_mfma_f32_16x16x32_bf16 v[60:63], v[156:159], v[188:191], v[60:63]
	v_mfma_f32_16x16x32_bf16 v[56:59], v[164:167], v[188:191], v[56:59]
	v_mfma_f32_16x16x32_bf16 v[44:47], v[156:159], v[196:199], v[44:47]
	v_mfma_f32_16x16x32_bf16 v[40:43], v[164:167], v[196:199], v[40:43]
	v_mfma_f32_16x16x32_bf16 v[28:31], v[156:159], v[206:209], v[28:31]
	v_mfma_f32_16x16x32_bf16 v[24:27], v[164:167], v[206:209], v[24:27]
	v_mfma_f32_16x16x32_bf16 v[12:15], v[156:159], v[214:217], v[12:15]
	v_mfma_f32_16x16x32_bf16 v[8:11], v[164:167], v[214:217], v[8:11]
	s_setprio 0
	s_setprio 1
	v_mfma_f32_16x16x32_bf16 v[52:55], v[168:171], v[184:187], v[52:55]
	v_mfma_f32_16x16x32_bf16 v[48:51], v[176:179], v[184:187], v[48:51]
	v_mfma_f32_16x16x32_bf16 v[36:39], v[168:171], v[192:195], v[36:39]
	v_mfma_f32_16x16x32_bf16 v[32:35], v[176:179], v[192:195], v[32:35]
	v_mfma_f32_16x16x32_bf16 v[20:23], v[168:171], v[202:205], v[20:23]
	v_mfma_f32_16x16x32_bf16 v[16:19], v[176:179], v[202:205], v[16:19]
	v_mfma_f32_16x16x32_bf16 v[4:7], v[168:171], v[210:213], v[4:7]
	v_mfma_f32_16x16x32_bf16 v[0:3], v[176:179], v[210:213], v[0:3]
	v_mfma_f32_16x16x32_bf16 v[52:55], v[172:175], v[188:191], v[52:55]
	v_mfma_f32_16x16x32_bf16 v[48:51], v[180:183], v[188:191], v[48:51]
	v_mfma_f32_16x16x32_bf16 v[36:39], v[172:175], v[196:199], v[36:39]
	v_mfma_f32_16x16x32_bf16 v[32:35], v[180:183], v[196:199], v[32:35]
	v_mfma_f32_16x16x32_bf16 v[20:23], v[172:175], v[206:209], v[20:23]
	v_mfma_f32_16x16x32_bf16 v[16:19], v[180:183], v[206:209], v[16:19]
	v_mfma_f32_16x16x32_bf16 v[4:7], v[172:175], v[214:217], v[4:7]
	v_mfma_f32_16x16x32_bf16 v[0:3], v[180:183], v[214:217], v[0:3]
	s_setprio 0
	s_barrier
; #define PG8_STAGE(bufoff, gbase, voff) do { _Pragma("unroll") for (int _i = 0; _i < 2; ++_i) \
;         __builtin_amdgcn_global_load_lds((const unsigned*)((const char*)(gbase) + (voff)[_i]), (PG8_LAS unsigned*)(lds + (bufoff) + ldsw + _i * 8192), 16, 0, 0); } while (0)
; #define PG8_LDA(dst, b, h) do { _Pragma("unroll") for (int m = 0; m < 4; ++m) _Pragma("unroll") for (int k = 0; k < 2; ++k) dst[m][k] = *(const PG8_LAS bf16x8*)(lds + PG8_SA(b, h) + aoff + m * 2048 + k * 1024); } while (0)
; #define PG8_LDB(dst, b, h) do { _Pragma("unroll") for (int n = 0; n < 2; ++n) _Pragma("unroll") for (int k = 0; k < 2; ++k) dst[n][k] = *(const PG8_LAS bf16x8*)(lds + PG8_SB(b, h) + boff + n * 2048 + k * 1024); } while (0)
; #define PG8_MMA(ai, bj, At, Bt) do { __builtin_amdgcn_s_setprio(1); _Pragma("unroll") for (int m = 0; m < 4; ++m) _Pragma("unroll") for (int n = 0; n < 2; ++n) _Pragma("unroll") for (int k = 0; k < 2; ++k) \
;         acc[ai][bj][m][n] = __builtin_amdgcn_mfma_f32_16x16x32_bf16(Bt[n][k], At[m][k], acc[ai][bj][m][n], 0, 0, 0); __builtin_amdgcn_s_setprio(0); } while (0)
; #define PG8_WAIT_V(n) asm volatile("s_waitcnt vmcnt(" #n ")" ::: "memory")
; #define PG8_WAIT_L(n) asm volatile("s_waitcnt lgkmcnt(" #n ")" ::: "memory")
; #define PG8_BAR __builtin_amdgcn_s_barrier()
; #define PG8_SCHED __builtin_amdgcn_sched_barrier(0)
; template <class Epi, class Sched, bool ALIGN_EPI = false, bool SP2 = false>
; __device__ __forceinline__ void gemm_phase(PG8_LAS unsigned char* lds, const Gemm g, const Sched& S, const Epi& E) {
;     ...
;             PG8_LDB(B0, 1, 0); PG8_LDB(B1, 1, 1); PG8_SCHED; PG8_LDA(At, 1, 0); PG8_STAGE(PG8_SA(0, 1), a2 + hstep, voffA);
;             PG8_WAIT_V(8); PG8_WAIT_L(0); PG8_BAR; PG8_MMA(0, 0, At, B0); PG8_MMA(0, 1, At, B1); PG8_BAR; PG8_SCHED;
	s_add_i32 s16, 0, 0x18000
	v_add_u32_e32 v155, s16, v149
	s_add_i32 s17, 0, 0x1c000
	ds_read_b128 v[144:147], v155
	ds_read_b128 v[156:159], v155 offset:1024
	ds_read_b128 v[160:163], v155 offset:2048
	ds_read_b128 v[164:167], v155 offset:3072
	v_add_u32_e32 v155, s17, v149
	ds_read_b128 v[168:171], v155
	ds_read_b128 v[172:175], v155 offset:1024
	ds_read_b128 v[176:179], v155 offset:2048
	ds_read_b128 v[180:183], v155 offset:3072
	s_add_u32 s46, s46, 0x4000
	s_addc_u32 s47, s47, 0
	s_mov_b32 m0, s52
	v_lshl_add_u64 v[230:231], s[46:47], 0, v[128:129]
	ds_read_b128 v[184:187], v153 offset:32768
	ds_read_b128 v[188:191], v153 offset:33792
	ds_read_b128 v[192:195], v153 offset:34816
	ds_read_b128 v[196:199], v153 offset:35840
	ds_read_b128 v[202:205], v153 offset:36864
	ds_read_b128 v[206:209], v153 offset:37888
	ds_read_b128 v[210:213], v153 offset:38912
	ds_read_b128 v[214:217], v153 offset:39936
	global_load_lds_dwordx4 v[230:231], off
	v_lshl_add_u64 v[230:231], s[46:47], 0, v[132:133]
	s_mov_b32 m0, s53
	s_nop 0
	global_load_lds_dwordx4 v[230:231], off
	s_waitcnt vmcnt(8)
	s_waitcnt lgkmcnt(0)
	s_barrier
	s_setprio 1
	s_waitcnt lgkmcnt(0)
	v_mfma_f32_16x16x32_bf16 v[124:127], v[144:147], v[184:187], v[124:127]
	v_mfma_f32_16x16x32_bf16 v[120:123], v[160:163], v[184:187], v[120:123]
	v_mfma_f32_16x16x32_bf16 v[108:111], v[144:147], v[192:195], v[108:111]
	v_mfma_f32_16x16x32_bf16 v[104:107], v[160:163], v[192:195], v[104:107]
	v_mfma_f32_16x16x32_bf16 v[92:95], v[144:147], v[202:205], v[92:95]
	v_mfma_f32_16x16x32_bf16 v[88:91], v[160:163], v[202:205], v[88:91]
	v_mfma_f32_16x16x32_bf16 v[76:79], v[144:147], v[210:213], v[76:79]
	v_mfma_f32_16x16x32_bf16 v[72:75], v[160:163], v[210:213], v[72:75]
	v_mfma_f32_16x16x32_bf16 v[124:127], v[156:159], v[188:191], v[124:127]
	v_mfma_f32_16x16x32_bf16 v[120:123], v[164:167], v[188:191], v[120:123]
	v_mfma_f32_16x16x32_bf16 v[108:111], v[156:159], v[196:199], v[108:111]
	v_mfma_f32_16x16x32_bf16 v[104:107], v[164:167], v[196:199], v[104:107]
	v_mfma_f32_16x16x32_bf16 v[92:95], v[156:159], v[206:209], v[92:95]
	v_mfma_f32_16x16x32_bf16 v[88:91], v[164:167], v[206:209], v[88:91]
	v_mfma_f32_16x16x32_bf16 v[76:79], v[156:159], v[214:217], v[76:79]
	v_mfma_f32_16x16x32_bf16 v[72:75], v[164:167], v[214:217], v[72:75]
	s_setprio 0
	s_setprio 1
	v_mfma_f32_16x16x32_bf16 v[116:119], v[168:171], v[184:187], v[116:119]
	v_mfma_f32_16x16x32_bf16 v[112:115], v[176:179], v[184:187], v[112:115]
	v_mfma_f32_16x16x32_bf16 v[100:103], v[168:171], v[192:195], v[100:103]
	v_mfma_f32_16x16x32_bf16 v[96:99], v[176:179], v[192:195], v[96:99]
	v_mfma_f32_16x16x32_bf16 v[84:87], v[168:171], v[202:205], v[84:87]
	v_mfma_f32_16x16x32_bf16 v[80:83], v[176:179], v[202:205], v[80:83]
	v_mfma_f32_16x16x32_bf16 v[68:71], v[168:171], v[210:213], v[68:71]
	v_mfma_f32_16x16x32_bf16 v[64:67], v[176:179], v[210:213], v[64:67]
	v_mfma_f32_16x16x32_bf16 v[116:119], v[172:175], v[188:191], v[116:119]
	v_mfma_f32_16x16x32_bf16 v[112:115], v[180:183], v[188:191], v[112:115]
	v_mfma_f32_16x16x32_bf16 v[100:103], v[172:175], v[196:199], v[100:103]
	v_mfma_f32_16x16x32_bf16 v[96:99], v[180:183], v[196:199], v[96:99]
	v_mfma_f32_16x16x32_bf16 v[84:87], v[172:175], v[206:209], v[84:87]
	v_mfma_f32_16x16x32_bf16 v[80:83], v[180:183], v[206:209], v[80:83]
	v_mfma_f32_16x16x32_bf16 v[68:71], v[172:175], v[214:217], v[68:71]
	v_mfma_f32_16x16x32_bf16 v[64:67], v[180:183], v[214:217], v[64:67]
	s_setprio 0
	s_barrier
; #define PG8_STAGE(bufoff, gbase, voff) do { _Pragma("unroll") for (int _i = 0; _i < 2; ++_i) \
;         __builtin_amdgcn_global_load_lds((const unsigned*)((const char*)(gbase) + (voff)[_i]), (PG8_LAS unsigned*)(lds + (bufoff) + ldsw + _i * 8192), 16, 0, 0); } while (0)
; #define PG8_LDA(dst, b, h) do { _Pragma("unroll") for (int m = 0; m < 4; ++m) _Pragma("unroll") for (int k = 0; k < 2; ++k) dst[m][k] = *(const PG8_LAS bf16x8*)(lds + PG8_SA(b, h) + aoff + m * 2048 + k * 1024); } while (0)
; #define PG8_MMA(ai, bj, At, Bt) do { __builtin_amdgcn_s_setprio(1); _Pragma("unroll") for (int m = 0; m < 4; ++m) _Pragma("unroll") for (int n = 0; n < 2; ++n) _Pragma("unroll") for (int k = 0; k < 2; ++k) \
;         acc[ai][bj][m][n] = __builtin_amdgcn_mfma_f32_16x16x32_bf16(Bt[n][k], At[m][k], acc[ai][bj][m][n], 0, 0, 0); __builtin_amdgcn_s_setprio(0); } while (0)
; #define PG8_WAIT_V(n) asm volatile("s_waitcnt vmcnt(" #n ")" ::: "memory")
; #define PG8_WAIT_L(n) asm volatile("s_waitcnt lgkmcnt(" #n ")" ::: "memory")
; #define PG8_BAR __builtin_amdgcn_s_barrier()
; #define PG8_SCHED __builtin_amdgcn_sched_barrier(0)
; template <class Epi, class Sched, bool ALIGN_EPI = false, bool SP2 = false>
; __device__ __forceinline__ void gemm_phase(PG8_LAS unsigned char* lds, const Gemm g, const Sched& S, const Epi& E) {
;     ...
;         for (int t = 0; t < nt; t += 2) {
;             const bool last = (t == nt - 2);
;             const char* a1 = cA + (size_t)(t + 1) * kstep;
;             const char* a2 = last ? nA : cA + (size_t)(t + 2) * kstep; const char* b2 = last ? nB : cB + (size_t)(t + 2) * kstep;
;             const char* a3 = a2 + kstep; const char* b3 = b2 + kstep;
;     ...
;             PG8_LDA(At, 1, 1); PG8_STAGE(PG8_SB(1, 0), b3, voffB); PG8_STAGE(PG8_SB(1, 1), b3 + hstep, voffB); PG8_STAGE(PG8_SA(1, 0), a3, voffA);
;             PG8_WAIT_V(8); PG8_WAIT_L(0); PG8_BAR; PG8_MMA(1, 0, At, B0); PG8_MMA(1, 1, At, B1); PG8_BAR; PG8_SCHED;
	s_add_i32 s16, s16, s49
	v_lshl_add_u64 v[218:219], v[218:219], 0, s[36:37]
	s_mov_b32 m0, s16
	ds_read_b128 v[184:187], v153 offset:49152
	ds_read_b128 v[188:191], v153 offset:50176
	ds_read_b128 v[192:195], v153 offset:51200
	ds_read_b128 v[196:199], v153 offset:52224
	ds_read_b128 v[202:205], v153 offset:53248
	ds_read_b128 v[206:209], v153 offset:54272
	ds_read_b128 v[210:213], v153 offset:55296
	ds_read_b128 v[214:217], v153 offset:56320
	global_load_lds_dwordx4 v[218:219], off
	v_lshl_add_u64 v[218:219], v[220:221], 0, s[36:37]
	s_add_i32 m0, s16, 0x2000
	s_add_i32 s16, s17, s49
	global_load_lds_dwordx4 v[218:219], off
	v_lshl_add_u64 v[218:219], v[222:223], 0, s[36:37]
	s_mov_b32 m0, s16
	s_nop 0
	global_load_lds_dwordx4 v[218:219], off
	v_lshl_add_u64 v[218:219], v[224:225], 0, s[36:37]
	s_add_i32 m0, s16, 0x2000
	s_nop 0
	global_load_lds_dwordx4 v[218:219], off
	v_lshl_add_u64 v[218:219], v[226:227], 0, s[100:101]
	s_mov_b32 m0, s54
	s_nop 0
	global_load_lds_dwordx4 v[218:219], off
	v_lshl_add_u64 v[218:219], v[228:229], 0, s[100:101]
	s_mov_b32 m0, s55
	s_nop 0
	global_load_lds_dwordx4 v[218:219], off
	s_waitcnt vmcnt(8)
	s_waitcnt lgkmcnt(0)
	s_barrier
	s_setprio 1
	s_waitcnt lgkmcnt(0)
	v_mfma_f32_16x16x32_bf16 v[60:63], v[144:147], v[184:187], v[60:63]
	v_mfma_f32_16x16x32_bf16 v[56:59], v[160:163], v[184:187], v[56:59]
	v_mfma_f32_16x16x32_bf16 v[44:47], v[144:147], v[192:195], v[44:47]
	v_mfma_f32_16x16x32_bf16 v[40:43], v[160:163], v[192:195], v[40:43]
	v_mfma_f32_16x16x32_bf16 v[28:31], v[144:147], v[202:205], v[28:31]
	v_mfma_f32_16x16x32_bf16 v[24:27], v[160:163], v[202:205], v[24:27]
	v_mfma_f32_16x16x32_bf16 v[12:15], v[144:147], v[210:213], v[12:15]
	v_mfma_f32_16x16x32_bf16 v[8:11], v[160:163], v[210:213], v[8:11]
	v_mfma_f32_16x16x32_bf16 v[60:63], v[156:159], v[188:191], v[60:63]
	v_mfma_f32_16x16x32_bf16 v[56:59], v[164:167], v[188:191], v[56:59]
	v_mfma_f32_16x16x32_bf16 v[44:47], v[156:159], v[196:199], v[44:47]
	v_mfma_f32_16x16x32_bf16 v[40:43], v[164:167], v[196:199], v[40:43]
	v_mfma_f32_16x16x32_bf16 v[28:31], v[156:159], v[206:209], v[28:31]
	v_mfma_f32_16x16x32_bf16 v[24:27], v[164:167], v[206:209], v[24:27]
	v_mfma_f32_16x16x32_bf16 v[12:15], v[156:159], v[214:217], v[12:15]
	v_mfma_f32_16x16x32_bf16 v[8:11], v[164:167], v[214:217], v[8:11]
	s_setprio 0
	s_setprio 1
	v_mfma_f32_16x16x32_bf16 v[52:55], v[168:171], v[184:187], v[52:55]
	v_mfma_f32_16x16x32_bf16 v[48:51], v[176:179], v[184:187], v[48:51]
	v_mfma_f32_16x16x32_bf16 v[36:39], v[168:171], v[192:195], v[36:39]
	v_mfma_f32_16x16x32_bf16 v[32:35], v[176:179], v[192:195], v[32:35]
	v_mfma_f32_16x16x32_bf16 v[20:23], v[168:171], v[202:205], v[20:23]
	v_mfma_f32_16x16x32_bf16 v[16:19], v[176:179], v[202:205], v[16:19]
	v_mfma_f32_16x16x32_bf16 v[4:7], v[168:171], v[210:213], v[4:7]
	v_mfma_f32_16x16x32_bf16 v[0:3], v[176:179], v[210:213], v[0:3]
	v_mfma_f32_16x16x32_bf16 v[52:55], v[172:175], v[188:191], v[52:55]
	v_mfma_f32_16x16x32_bf16 v[48:51], v[180:183], v[188:191], v[48:51]
	v_mfma_f32_16x16x32_bf16 v[36:39], v[172:175], v[196:199], v[36:39]
	v_mfma_f32_16x16x32_bf16 v[32:35], v[180:183], v[196:199], v[32:35]
	v_mfma_f32_16x16x32_bf16 v[20:23], v[172:175], v[206:209], v[20:23]
	v_mfma_f32_16x16x32_bf16 v[16:19], v[180:183], v[206:209], v[16:19]
	v_mfma_f32_16x16x32_bf16 v[4:7], v[172:175], v[214:217], v[4:7]
	v_mfma_f32_16x16x32_bf16 v[0:3], v[180:183], v[214:217], v[0:3]
	s_setprio 0
	s_barrier
	s_add_u32 s44, s44, 0x10000
	s_addc_u32 s45, s45, 0
	s_add_u32 s68, s68, 0x100
	s_addc_u32 s69, s69, 0
	s_cmp_ge_i32 s70, s57
	s_mov_b32 s46, s70
	s_cbranch_scc0 .LBB0_1104
